# stack: SWA bias straight-line + SWA bias/sink loads hoisted out of serialized waits + fill_rstd split across both workgroup halves
# speedup vs baseline: 1.0119x; 1.0037x over previous
.LBB0_200:
	s_or_b64 exec, exec, s[6:7]
	s_and_b64 s[2:3], s[4:5], exec
	s_cselect_b32 s9, 0, s52
	s_cmp_eq_u32 s9, 1
	s_cselect_b64 s[4:5], -1, 0
	s_and_b64 s[2:3], s[4:5], exec
	s_cselect_b32 s0, 13, 6
	s_cmp_eq_u32 s9, 0
	s_cselect_b64 s[6:7], -1, 0
	s_and_b64 s[2:3], s[6:7], exec
	s_mul_i32 s2, s52, 0x180000
	s_mov_b32 s3, s1
	v_writelane_b32 v255, s2, 4
	s_cselect_b32 s25, 12, s0
	s_mov_b32 s8, 0
	s_mov_b32 s12, 0
	v_writelane_b32 v255, s3, 5
	s_mov_b32 s24, 0
	s_mov_b32 s16, 0
	s_mov_b32 s3, 0
	s_mov_b32 s2, 0
	s_mov_b32 s30, s1
	v_and_b32_e32 v0, 0xff, v195
	v_lshrrev_b32_e32 v251, 8, v195
	s_movk_i32 s10, 0x100
	s_lshl_b32 s0, s25, 7
	s_nop 0
	v_cmp_gt_i32_e32 vcc, s10, v0
	s_and_saveexec_b64 s[10:11], vcc
	s_cbranch_execz .LBB0_205
	s_ashr_i32 s13, s12, 31
	s_add_u32 s14, s62, s12
	s_addc_u32 s15, s63, s13
	v_readlane_b32 s12, v255, 4
	v_readlane_b32 s13, v255, 5
	s_lshl_b64 s[12:13], s[12:13], 2
	s_add_u32 s12, s14, s12
	s_addc_u32 s13, s15, s13
	s_lshl_b32 s17, s25, 3
	s_abs_i32 s18, s17
	v_cvt_f32_u32_e32 v2, s18
	s_sub_i32 s14, 0, s18
	s_lshl_b32 s19, s25, 4
	s_bfe_i32 s26, s25, 0x1001c
	v_rcp_iflag_f32_e32 v3, v2
	v_mov_b32_e32 v2, 0x20400
	v_lshl_add_u32 v2, v0, 2, v2
	v_lshl_add_u32 v2, v251, 10, v2
	v_mul_f32_e32 v3, 0x4f7ffffe, v3
	v_cvt_u32_f32_e32 v3, v3
	s_nop 0
	v_readfirstlane_b32 s15, v3
	s_mul_i32 s14, s14, s15
	s_mul_hi_u32 s14, s15, s14
	s_add_i32 s28, s15, s14
	s_mov_b64 s[14:15], s[88:89]
	v_readfirstlane_b32 s100, v251
	s_mul_i32 s100, s100, s94
	s_add_u32 s14, s14, s100
	s_addc_u32 s15, s15, 0
	s_branch .LBB0_203

.LBB0_203:
	v_mov_b64_e32 v[4:5], s[0:1]
	v_cmp_ge_i64_e32 vcc, s[14:15], v[4:5]
	s_mov_b64 s[20:21], -1
	s_cbranch_vccnz .LBB0_202
	s_ashr_i32 s20, s14, 31
	s_lshr_b32 s20, s20, 29
	s_add_i32 s20, s14, s20
	s_ashr_i32 s21, s20, 3
	s_and_b32 s20, s20, -8
	s_sub_i32 s20, s14, s20
	s_lshr_b32 s29, s20, 31
	s_or_b32 s29, s19, s29
	s_mul_i32 s20, s29, s20
	s_add_i32 s20, s20, s21
	s_abs_i32 s29, s20
	s_mul_hi_u32 s31, s29, s28
	s_mul_i32 s34, s31, s18
	s_ashr_i32 s21, s20, 31
	s_sub_i32 s29, s29, s34
	s_xor_b32 s21, s21, s26
	s_add_i32 s34, s31, 1
	s_sub_i32 s35, s29, s18
	s_cmp_ge_u32 s29, s18
	s_cselect_b32 s31, s34, s31
	s_cselect_b32 s29, s35, s29
	s_add_i32 s34, s31, 1
	s_cmp_ge_u32 s29, s18
	s_cselect_b32 s29, s34, s31
	s_xor_b32 s29, s29, s21
	s_sub_i32 s21, s29, s21
	s_lshl_b32 s29, s21, 3
	s_sub_i32 s31, 0x80, s29
	s_min_i32 s31, s31, 8
	s_abs_i32 s31, s31
	v_cvt_f32_u32_e32 v3, s31
	s_sub_i32 s34, 0, s31
	s_mul_i32 s21, s21, s17
	s_sub_i32 s20, s20, s21
	v_rcp_iflag_f32_e32 v3, v3
	s_ashr_i32 s21, s20, 31
	s_abs_i32 s20, s20
	v_mul_f32_e32 v3, 0x4f7ffffe, v3
	v_cvt_u32_f32_e32 v3, v3
	s_nop 0
	v_readfirstlane_b32 s35, v3
	s_mul_i32 s34, s34, s35
	s_mul_hi_u32 s34, s35, s34
	s_add_i32 s35, s35, s34
	s_mul_hi_u32 s34, s20, s35
	s_mul_i32 s34, s34, s31
	s_sub_i32 s20, s20, s34
	s_sub_i32 s34, s20, s31
	s_cmp_ge_u32 s20, s31
	s_cselect_b32 s20, s34, s20
	s_sub_i32 s34, s20, s31
	s_cmp_ge_u32 s20, s31
	s_cselect_b32 s20, s34, s20
	s_xor_b32 s20, s20, s21
	s_sub_i32 s20, s20, s21
	s_add_i32 s20, s20, s29
	v_lshl_add_u32 v4, s20, 8, v0
	v_ashrrev_i32_e32 v5, 31, v4
	v_lshlrev_b64 v[4:5], 6, v[4:5]
	s_waitcnt vmcnt(1)
	v_lshl_add_u64 v[16:17], s[12:13], 0, v[4:5]
	global_load_dwordx4 v[4:7], v[16:17], off
	global_load_dwordx4 v[8:11], v[16:17], off offset:32
	global_load_dwordx4 v[12:15], v[16:17], off offset:16
	s_nop 0
	global_load_dwordx4 v[16:19], v[16:17], off offset:48
	s_add_u32 s14, s14, s94
	s_addc_u32 s15, s15, s77
	s_add_u32 s14, s14, s94
	s_addc_u32 s15, s15, s77
	s_mov_b64 s[20:21], 0
	s_waitcnt vmcnt(3)
	v_mov_b32_e32 v20, v4
	s_waitcnt vmcnt(2)
	v_mov_b32_e32 v21, v8
	v_mov_b32_e32 v8, v5
	v_mov_b32_e32 v4, v6
	v_mov_b32_e32 v5, v10
	v_mov_b32_e32 v10, v7
	s_waitcnt vmcnt(1)
	v_mov_b32_e32 v6, v12
	s_waitcnt vmcnt(0)
	v_mov_b32_e32 v7, v16
	v_mov_b32_e32 v16, v13
	v_mov_b32_e32 v12, v14
	v_mov_b32_e32 v13, v18
	v_mov_b32_e32 v18, v15
	v_pk_add_f32 v[8:9], v[20:21], v[8:9]
	v_pk_add_f32 v[4:5], v[4:5], v[10:11]
	v_pk_add_f32 v[6:7], v[6:7], v[16:17]
	v_pk_add_f32 v[10:11], v[12:13], v[18:19]
	v_pk_add_f32 v[4:5], v[8:9], v[4:5]
	v_pk_add_f32 v[6:7], v[6:7], v[10:11]
	s_nop 0
	v_pk_add_f32 v[4:5], v[4:5], v[6:7]
	s_nop 0
	v_add_f32_e32 v3, v4, v5
	v_mov_b32_e32 v4, 0x358637bd
	v_fmamk_f32 v3, v3, 0x3a800000, v4
	v_mul_f32_e32 v4, 0x4b800000, v3
	v_cmp_gt_f32_e32 vcc, s97, v3
	s_nop 1
	v_cndmask_b32_e32 v3, v3, v4, vcc
	v_rsq_f32_e32 v3, v3
	s_nop 0
	v_mul_f32_e32 v4, 0x45800000, v3
	v_cndmask_b32_e32 v3, v3, v4, vcc
	ds_write_b32 v2, v3
	v_add_u32_e32 v2, 0x800, v2
	s_branch .LBB0_202

.LBB0_458:
	v_mov_b32_e32 v6, v195
	s_and_b32 s2, s19, 7
	v_readfirstlane_b32 s24, v6
	s_ashr_i32 s13, s24, 6
	s_lshl_b32 s0, s2, 8
	s_lshl_b32 s12, s13, 5
	s_ashr_i32 s4, s19, 7
	v_and_b32_e32 v102, 31, v6
	s_add_i32 s15, s12, s0
	v_or_b32_e32 v2, s15, v102
	s_ashr_i32 s5, s4, 31
	s_lshl_b64 s[36:37], s[4:5], 12
	v_ashrrev_i32_e32 v3, 31, v2
	v_lshl_add_u64 v[2:3], s[36:37], 0, v[2:3]
	v_readlane_b32 s4, v255, 16
	s_bfe_u32 s3, s19, 0x40003
	v_lshlrev_b64 v[2:3], 11, v[2:3]
	v_readlane_b32 s5, v255, 17
	v_bfe_u32 v101, v6, 5, 1
	s_lshl_b32 s0, s3, 7
	v_lshl_add_u64 v[2:3], s[4:5], 0, v[2:3]
	v_lshl_add_u64 v[2:3], v[2:3], 0, s[0:1]
	v_lshlrev_b32_e32 v0, 4, v101
	v_lshl_add_u64 v[2:3], v[2:3], 0, v[0:1]
	global_load_dwordx4 v[80:83], v[2:3], off
	global_load_dwordx4 v[84:87], v[2:3], off offset:32
	global_load_dwordx4 v[88:91], v[2:3], off offset:64
	global_load_dwordx4 v[92:95], v[2:3], off offset:96
	s_lshl_b32 s100, s3, 2
	v_mov_b32_e32 v245, s100
	global_load_dword v245, v245, s[10:11]
	v_cmp_gt_i32_e32 vcc, s27, v6
	s_and_saveexec_b64 s[4:5], vcc
	s_cbranch_execz .LBB0_462
	v_cmp_lt_i32_e32 vcc, 15, v6
	v_mov_b32_e32 v2, v6
	s_and_saveexec_b64 s[6:7], vcc
	s_cbranch_execz .LBB0_461
	v_cvt_f32_u32_e32 v2, v6
	v_mul_f32_e32 v2, 0x3d800000, v2
	v_cmp_gt_f32_e32 vcc, s97, v2
	s_nop 1
	v_cndmask_b32_e64 v3, 0, 32, vcc
	v_ldexp_f32 v2, v2, v3
	v_log_f32_e32 v2, v2
	v_mov_b32_e32 v3, 0x41b17218
	v_cndmask_b32_e32 v3, 0, v3, vcc
	v_mul_f32_e32 v4, 0x3f317217, v2
	v_fma_f32 v4, v2, s44, -v4
	v_fmac_f32_e32 v4, 0x3377d1cf, v2
	v_fmac_f32_e32 v4, 0x3f317217, v2
	v_cmp_lt_f32_e64 vcc, |v2|, s45
	s_nop 1
	v_cndmask_b32_e32 v2, v2, v4, vcc
	v_sub_f32_e32 v2, v2, v3
	v_div_scale_f32 v3, s[16:17], s46, s46, v2
	v_rcp_f32_e32 v4, v3
	v_div_scale_f32 v5, vcc, v2, s46, v2
	v_fma_f32 v7, -v3, v4, 1.0
	v_fmac_f32_e32 v4, v7, v4
	v_mul_f32_e32 v7, v5, v4
	v_fma_f32 v8, -v3, v7, v5
	v_fmac_f32_e32 v7, v8, v4
	v_fma_f32 v3, -v3, v7, v5
	v_div_fmas_f32 v3, v3, v4, v7
	v_div_fixup_f32 v2, v3, s46, v2
	v_mul_f32_e32 v2, 0x41800000, v2
	v_cvt_i32_f32_e32 v2, v2
	v_min_i32_e32 v2, 15, v2
	v_add_u32_e32 v2, 16, v2
.LBB0_461:
	s_or_b64 exec, exec, s[6:7]
	v_lshl_or_b32 v2, v2, 4, s3
	v_ashrrev_i32_e32 v3, 31, v2
	v_lshl_add_u64 v[2:3], v[2:3], 2, s[8:9]
	global_load_dword v243, v[2:3], off
	v_lshl_add_u32 v244, v6, 2, 0
	v_add_u32_e32 v244, 0x1ac40, v244
.LBB0_462:
	s_or_b64 exec, exec, s[4:5]
	v_ashrrev_i32_e32 v2, 3, v6
	v_ashrrev_i32_e32 v3, 31, v2
	v_lshl_add_u64 v[4:5], s[36:37], 0, v[2:3]
	v_readlane_b32 s6, v255, 20
	s_and_b32 s0, s18, 7
	v_lshlrev_b64 v[8:9], 9, v[4:5]
	v_readlane_b32 s7, v255, 21
	s_mul_i32 s29, s0, 0xc000
	s_lshl_b32 s30, s0, 2
	s_mul_i32 s31, s0, 0x9000
	s_lshl_b32 s20, s0, 8
	s_lshl_b32 s0, s3, 4
	v_lshl_add_u64 v[4:5], s[6:7], 0, v[8:9]
	v_readlane_b32 s6, v255, 18
	s_and_b32 s14, s0, 0xc0
	v_readlane_b32 s7, v255, 19
	s_lshl_b32 s0, s14, 1
	v_lshlrev_b32_e32 v3, 4, v6
	v_lshl_add_u64 v[8:9], s[6:7], 0, v[8:9]
	v_lshl_add_u64 v[10:11], v[4:5], 0, s[0:1]
	v_and_b32_e32 v4, 0x70, v3
	v_lshl_add_u64 v[8:9], v[8:9], 0, s[0:1]
	v_mov_b32_e32 v5, v1
	s_movk_i32 s0, 0xc0
	v_mad_u64_u32 v[40:41], s[6:7], v2, s0, v[4:5]
	s_lshl_b32 s4, s2, 2
	s_and_b32 s5, s24, 0x3fffffc0
	v_add_u32_e32 v42, 0, v40
	s_movk_i32 s0, 0xffd0
	s_ashr_i32 s21, s24, 7
	s_or_b32 s24, s4, 3
	v_mad_u64_u32 v[44:45], s[6:7], v2, s0, v[42:43]
	s_lshl_b32 s0, s5, 2
	v_lshl_add_u64 v[96:97], v[8:9], 0, v[4:5]
	v_lshl_add_u64 v[98:99], v[10:11], 0, v[4:5]
	s_add_i32 s28, s0, 0
	s_lshl_b32 s0, s24, 15
	s_or_b32 s5, s4, 2
	v_lshl_add_u64 v[8:9], v[96:97], 0, s[0:1]
	v_lshl_add_u64 v[12:13], v[98:99], 0, s[0:1]
	s_lshl_b32 s0, s5, 15
	s_or_b32 s6, s4, 1
	v_lshl_add_u64 v[16:17], v[96:97], 0, s[0:1]
	v_lshl_add_u64 v[20:21], v[98:99], 0, s[0:1]
	s_lshl_b32 s0, s6, 15
	v_lshl_add_u64 v[24:25], v[96:97], 0, s[0:1]
	v_lshl_add_u64 v[28:29], v[98:99], 0, s[0:1]
	s_lshl_b32 s0, s2, 17
	v_lshl_add_u64 v[32:33], v[96:97], 0, s[0:1]
	v_lshl_add_u64 v[36:37], v[98:99], 0, s[0:1]
	global_load_dwordx4 v[8:11], v[8:9], off
	v_and_b32_e32 v7, 63, v6
	global_load_dwordx4 v[16:19], v[16:17], off
	s_lshl_b32 s16, s3, 6
	global_load_dwordx4 v[20:23], v[20:21], off
	s_add_i32 s17, s30, -1
	global_load_dwordx4 v[24:27], v[24:25], off
	s_add_i32 s28, s28, 0x1a440
	global_load_dwordx4 v[28:31], v[28:29], off
	v_lshlrev_b32_e32 v3, 2, v101
	global_load_dwordx4 v[32:35], v[32:33], off
	s_nop 0
	global_load_dwordx4 v[36:39], v[36:37], off
	s_nop 0
	global_load_dwordx4 v[12:15], v[12:13], off
	s_mul_i32 s0, s24, 52
	s_lshr_b32 s0, s0, 8
	s_mul_i32 s0, s0, 5
	s_sub_i32 s0, s24, s0
	s_and_b32 s0, s0, 0xff
	s_mul_i32 s7, s0, 0x2400
	v_add_u32_e32 v5, s7, v44
	s_mulk_i32 s0, 0x3000
	s_waitcnt vmcnt(7)
	v_cmp_gt_i32_e32 vcc, s27, v195
	s_and_saveexec_b64 s[100:101], vcc
	v_mul_f32_e32 v243, 0x3fb8aa3b, v243
	ds_write_b32 v244, v243
	s_or_b64 exec, exec, s[100:101]
	ds_write_b128 v5, v[8:11]
	v_add_u32_e32 v5, s0, v42
	s_mul_i32 s0, s5, 52
	s_lshr_b32 s0, s0, 8
	s_mul_i32 s0, s0, 5
	s_sub_i32 s0, s5, s0
	s_and_b32 s0, s0, 0xff
	s_mul_i32 s5, s0, 0x2400
	s_waitcnt vmcnt(0)
	ds_write_b128 v5, v[12:15] offset:46080
	v_add_u32_e32 v5, s5, v44
	s_mulk_i32 s0, 0x3000
	ds_write_b128 v5, v[16:19]
	v_add_u32_e32 v5, s0, v42
	s_mul_i32 s0, s6, 52
	s_lshr_b32 s0, s0, 8
	s_mul_i32 s0, s0, 5
	s_sub_i32 s0, s6, s0
	s_and_b32 s0, s0, 0xff
	s_mul_i32 s5, s0, 0x2400
	ds_write_b128 v5, v[20:23] offset:46080
	v_add_u32_e32 v5, s5, v44
	s_mulk_i32 s0, 0x3000
	ds_write_b128 v5, v[24:27]
	v_add_u32_e32 v5, s0, v42
	s_mul_i32 s0, s2, 0xd0
	s_lshr_b32 s0, s0, 8
	s_mul_i32 s0, s0, 5
	s_sub_i32 s0, s4, s0
	s_and_b32 s0, s0, 0xff
	s_mul_i32 s4, s0, 0x2400
	ds_write_b128 v5, v[28:31] offset:46080
	v_add_u32_e32 v5, s4, v44
	s_mulk_i32 s0, 0x3000
	v_lshrrev_b32_e32 v6, 2, v6
	ds_write_b128 v5, v[32:35]
	v_add_u32_e32 v5, s0, v42
	s_lshl_b32 s0, s13, 2
	v_and_or_b32 v6, v6, 3, v3
	s_add_i32 s26, s0, 0
	v_mul_u32_u24_e32 v6, 0xc0, v6
	s_mul_i32 s0, s21, 0x3000
	s_movk_i32 s34, 0x90
	v_or_b32_e32 v6, s0, v6
	s_add_i32 s0, s31, 0xffffdc00
	v_mul_lo_u32 v2, v2, s34
	v_add3_u32 v120, s0, v2, v4
	s_mul_i32 s0, s21, 0x2400
	ds_write_b128 v5, v[36:39] offset:46080
	v_mul_u32_u24_e32 v5, 0x90, v102
	s_add_i32 s0, s0, s31
	v_add3_u32 v122, s0, v5, v0
	s_sub_i32 s0, s12, 59
	v_add_u32_e32 v2, s0, v102
	s_lshl_b32 s34, s21, 6
	v_sub_u32_e32 v2, v2, v3
	v_subrev_u32_e32 v123, s34, v2
	v_add_u32_e32 v2, s12, v102
	v_sub_u32_e32 v2, v2, v3
	v_lshlrev_b32_e32 v8, 2, v102
	v_subrev_u32_e32 v2, s34, v2
	v_mov_b32_e32 v4, 0x1ac40
	v_cmp_eq_u32_e64 s[6:7], 0, v7
	v_cmp_gt_u32_e64 s[4:5], 32, v7
	v_lshlrev_b32_e32 v9, 1, v7
	v_lshlrev_b32_e32 v7, 3, v7
	v_lshl_add_u32 v124, v2, 2, v4
	v_lshl_or_b32 v2, s13, 7, v8
	v_add_u32_e32 v103, s28, v0
	v_and_b32_e32 v9, 32, v9
	v_and_b32_e32 v7, 24, v7
	v_sub_u32_e32 v0, v2, v0
	s_lshl_b32 s0, s21, 8
	v_or3_b32 v6, v6, v9, v7
	v_subrev_u32_e32 v126, s0, v0
	v_sub_u32_e32 v0, v3, v102
	v_mov_b32_e32 v14, v1
	v_mov_b32_e32 v15, v1
	v_add_u32_e32 v104, s28, v8
	v_add_u32_e32 v100, 0xde40, v6
	v_add_u32_e32 v105, 0xd840, v6
	v_add_u32_e32 v106, 0xde00, v6
	v_add_u32_e32 v107, 0xd800, v6
	v_add_u32_e32 v108, 0xd240, v6
	v_add_u32_e32 v109, 0xcc40, v6
	v_add_u32_e32 v110, 0xd200, v6
	v_add_u32_e32 v111, 0xcc00, v6
	v_add_u32_e32 v112, 0xc640, v6
	v_add_u32_e32 v113, 0xc040, v6
	v_add_u32_e32 v114, 0xc600, v6
	v_add_u32_e32 v115, 0xc000, v6
	v_add_u32_e32 v116, 0xba40, v6
	v_add_u32_e32 v117, 0xb440, v6
	v_add_u32_e32 v118, 0xba00, v6
	v_add_u32_e32 v119, 0xb400, v6
	v_add_u32_e32 v121, 0x8400, v40
	v_subrev_u32_e32 v127, s12, v0
	v_mov_b32_e32 v0, v1
	v_mov_b32_e32 v2, v1
	v_mov_b32_e32 v3, v1
	v_mov_b32_e32 v4, v1
	v_mov_b32_e32 v5, v1
	v_mov_b32_e32 v6, v1
	v_mov_b32_e32 v7, v1
	v_mov_b32_e32 v8, v1
	v_mov_b32_e32 v9, v1
	v_mov_b32_e32 v10, v1
	v_mov_b32_e32 v11, v1
	v_mov_b32_e32 v12, v1
	v_mov_b32_e32 v13, v1
	v_mov_b64_e32 v[30:31], v[14:15]
	v_mov_b64_e32 v[46:47], v[14:15]
	s_add_i32 s24, s15, 0xffffff81
	s_mov_b32 s25, 0
	s_add_i32 s26, s26, 0x1a400
	s_add_i32 s28, s21, s30
	s_add_i32 s29, s29, 0
	v_mov_b32_e32 v128, 0xff800000
	v_mov_b32_e32 v125, 0
	s_mov_b32 s35, 0
	v_mov_b64_e32 v[28:29], v[12:13]
	v_mov_b64_e32 v[26:27], v[10:11]
	v_mov_b64_e32 v[24:25], v[8:9]
	v_mov_b64_e32 v[22:23], v[6:7]
	v_mov_b64_e32 v[20:21], v[4:5]
	v_mov_b64_e32 v[18:19], v[2:3]
	v_mov_b64_e32 v[16:17], v[0:1]
	v_mov_b64_e32 v[44:45], v[12:13]
	v_mov_b64_e32 v[42:43], v[10:11]
	v_mov_b64_e32 v[40:41], v[8:9]
	v_mov_b64_e32 v[38:39], v[6:7]
	v_mov_b64_e32 v[36:37], v[4:5]
	v_mov_b64_e32 v[34:35], v[2:3]
	v_mov_b64_e32 v[32:33], v[0:1]
	s_waitcnt lgkmcnt(0)
	s_barrier

.LBB0_542:
	s_waitcnt vmcnt(0)
	v_and_b32_e32 v2, 64, v200
	v_xor_b32_e32 v0, 32, v200
	v_add_u32_e32 v2, 64, v2
	v_cmp_lt_i32_e32 vcc, v0, v2
	s_nop 1
	v_cndmask_b32_e32 v0, v200, v0, vcc
	v_lshlrev_b32_e32 v100, 2, v0
	ds_bpermute_b32 v0, v100, v125
	s_and_saveexec_b64 s[6:7], s[4:5]
	s_cbranch_execz .LBB0_544
	s_lshl_b32 s0, s3, 2
	s_nop 0
	s_nop 0
	s_waitcnt lgkmcnt(0)
	v_add_f32_e32 v0, v125, v0
	s_waitcnt vmcnt(0)
	v_fma_f32 v2, v245, s68, -v51
	v_exp_f32_e32 v2, v2
	s_nop 0
	v_add_f32_e32 v0, v0, v2
	v_div_scale_f32 v2, s[4:5], v0, v0, 1.0
	v_rcp_f32_e32 v3, v2
	v_div_scale_f32 v4, vcc, 1.0, v0, 1.0
	v_fma_f32 v5, -v2, v3, 1.0
	v_fmac_f32_e32 v3, v5, v3
	v_mul_f32_e32 v5, v4, v3
	v_fma_f32 v6, -v2, v5, v4
	v_fmac_f32_e32 v5, v6, v3
	v_fma_f32 v2, -v2, v5, v4
	v_div_fmas_f32 v2, v2, v3, v5
	v_div_fixup_f32 v0, v2, v0, 1.0
	ds_write_b32 v104, v0
.LBB0_544:
	s_or_b64 exec, exec, s[6:7]
	s_ashr_i32 s0, s15, 31
	s_add_u32 s4, s36, s15
	s_addc_u32 s5, s37, s0
	s_lshl_b64 s[4:5], s[4:5], 11
	v_readlane_b32 s0, v255, 22
	s_add_u32 s0, s0, s4
	v_readlane_b32 s4, v255, 23
	s_addc_u32 s5, s4, s5
	s_lshl_b32 s12, s16, 1
	ds_read_b128 v[2:5], v103
	ds_read_b128 v[6:9], v103 offset:32
	ds_read_b128 v[10:13], v103 offset:64
	ds_read_b128 v[48:51], v103 offset:96
	s_add_u32 s4, s0, s12
	s_addc_u32 s5, s5, 0
	s_waitcnt lgkmcnt(4)
	v_lshlrev_b32_e32 v0, 1, v102
	v_lshl_add_u64 v[14:15], s[4:5], 0, v[0:1]
	s_waitcnt lgkmcnt(3)
	v_mul_f32_e32 v0, v32, v2
	v_cvt_pk_bf16_f32 v32, v0, s0
	v_lshlrev_b32_e32 v0, 13, v101
	v_lshl_add_u64 v[14:15], v[14:15], 0, v[0:1]
	v_mul_f32_e32 v0, v16, v2
	v_cvt_pk_bf16_f32 v0, v0, s0
	global_store_short v[14:15], v0, off offset:64
	v_mul_f32_e32 v0, v33, v3
	v_cvt_pk_bf16_f32 v0, v0, s0
	global_store_short v[14:15], v0, off offset:2048
	v_mul_f32_e32 v0, v17, v3
	v_cvt_pk_bf16_f32 v0, v0, s0
	global_store_short v[14:15], v0, off offset:2112
	v_mul_f32_e32 v0, v34, v4
	v_cvt_pk_bf16_f32 v0, v0, s0
	s_movk_i32 s0, 0x1000
	v_add_co_u32_e32 v2, vcc, s0, v14
	global_store_short v[14:15], v32, off
	s_nop 0
	v_addc_co_u32_e32 v3, vcc, 0, v15, vcc
	global_store_short v[2:3], v0, off
	v_mul_f32_e32 v0, v18, v4
	v_cvt_pk_bf16_f32 v0, v0, s0
	global_store_short v[2:3], v0, off offset:64
	v_mul_f32_e32 v0, v35, v5
	v_cvt_pk_bf16_f32 v0, v0, s0
	global_store_short v[2:3], v0, off offset:2048
	v_mul_f32_e32 v0, v19, v5
	v_cvt_pk_bf16_f32 v0, v0, s0
	global_store_short v[2:3], v0, off offset:2112
	s_waitcnt lgkmcnt(2)
	v_mul_f32_e32 v0, v36, v6
	v_cvt_pk_bf16_f32 v0, v0, s0
	s_movk_i32 s0, 0x4000
	v_add_co_u32_e32 v2, vcc, s0, v14
	s_movk_i32 s0, 0x5000
	s_nop 0
	v_addc_co_u32_e32 v3, vcc, 0, v15, vcc
	v_add_co_u32_e32 v4, vcc, s0, v14
	s_xor_b32 s24, s2, 15
	s_nop 0
	v_addc_co_u32_e32 v5, vcc, 0, v15, vcc
	global_store_short v[4:5], v0, off offset:-4096
	v_mul_f32_e32 v0, v20, v6
	v_cvt_pk_bf16_f32 v0, v0, s0
	global_store_short v[2:3], v0, off offset:64
	v_mul_f32_e32 v0, v37, v7
	v_cvt_pk_bf16_f32 v0, v0, s0
	global_store_short v[2:3], v0, off offset:2048
	v_mul_f32_e32 v0, v21, v7
	v_cvt_pk_bf16_f32 v0, v0, s0
	global_store_short v[2:3], v0, off offset:2112
	v_mul_f32_e32 v0, v38, v8
	v_cvt_pk_bf16_f32 v0, v0, s0
	global_store_short v[4:5], v0, off
	v_mul_f32_e32 v0, v22, v8
	v_cvt_pk_bf16_f32 v0, v0, s0
	global_store_short v[4:5], v0, off offset:64
	v_mul_f32_e32 v0, v39, v9
	v_cvt_pk_bf16_f32 v0, v0, s0
	global_store_short v[4:5], v0, off offset:2048
	v_mul_f32_e32 v0, v23, v9
	v_cvt_pk_bf16_f32 v0, v0, s0
	global_store_short v[4:5], v0, off offset:2112
	s_waitcnt lgkmcnt(1)
	v_mul_f32_e32 v0, v40, v10
	v_cvt_pk_bf16_f32 v0, v0, s0
	s_mov_b32 s0, 0x8000
	v_add_co_u32_e32 v2, vcc, s0, v14
	s_mov_b32 s0, 0x9000
	s_nop 0
	v_addc_co_u32_e32 v3, vcc, 0, v15, vcc
	v_add_co_u32_e32 v4, vcc, s0, v14
	s_lshl_b32 s15, s24, 8
	s_nop 0
	v_addc_co_u32_e32 v5, vcc, 0, v15, vcc
	global_store_short v[4:5], v0, off offset:-4096
	v_mul_f32_e32 v0, v24, v10
	v_cvt_pk_bf16_f32 v0, v0, s0
	global_store_short v[2:3], v0, off offset:64
	v_mul_f32_e32 v0, v41, v11
	v_cvt_pk_bf16_f32 v0, v0, s0
	global_store_short v[2:3], v0, off offset:2048
	v_mul_f32_e32 v0, v25, v11
	v_cvt_pk_bf16_f32 v0, v0, s0
	global_store_short v[2:3], v0, off offset:2112
	v_mul_f32_e32 v0, v42, v12
	v_cvt_pk_bf16_f32 v0, v0, s0
	global_store_short v[4:5], v0, off
	v_mul_f32_e32 v0, v26, v12
	v_cvt_pk_bf16_f32 v0, v0, s0
	global_store_short v[4:5], v0, off offset:64
	v_mul_f32_e32 v0, v43, v13
	v_cvt_pk_bf16_f32 v0, v0, s0
	global_store_short v[4:5], v0, off offset:2048
	v_mul_f32_e32 v0, v27, v13
	v_cvt_pk_bf16_f32 v0, v0, s0
	global_store_short v[4:5], v0, off offset:2112
	s_waitcnt lgkmcnt(0)
	v_mul_f32_e32 v0, v44, v48
	v_cvt_pk_bf16_f32 v0, v0, s0
	s_mov_b32 s0, 0xc000
	v_add_co_u32_e32 v2, vcc, s0, v14
	s_mov_b32 s0, 0xd000
	s_nop 0
	v_addc_co_u32_e32 v3, vcc, 0, v15, vcc
	v_add_co_u32_e32 v4, vcc, s0, v14
	v_readlane_b32 s4, v255, 16
	s_nop 0
	v_addc_co_u32_e32 v5, vcc, 0, v15, vcc
	global_store_short v[4:5], v0, off offset:-4096
	v_mul_f32_e32 v0, v28, v48
	v_cvt_pk_bf16_f32 v0, v0, s0
	global_store_short v[2:3], v0, off offset:64
	v_mul_f32_e32 v0, v45, v49
	v_cvt_pk_bf16_f32 v0, v0, s0
	global_store_short v[2:3], v0, off offset:2048
	v_mul_f32_e32 v0, v29, v49
	v_cvt_pk_bf16_f32 v0, v0, s0
	global_store_short v[2:3], v0, off offset:2112
	v_mul_f32_e32 v0, v46, v50
	v_cvt_pk_bf16_f32 v0, v0, s0
	global_store_short v[4:5], v0, off
	v_mul_f32_e32 v0, v30, v50
	v_cvt_pk_bf16_f32 v0, v0, s0
	global_store_short v[4:5], v0, off offset:64
	v_mul_f32_e32 v0, v47, v51
	v_cvt_pk_bf16_f32 v0, v0, s0
	global_store_short v[4:5], v0, off offset:2048
	v_mul_f32_e32 v0, v31, v51
	v_cvt_pk_bf16_f32 v0, v0, s0
	global_store_short v[4:5], v0, off offset:2112
	v_mov_b32_e32 v4, v195
	v_readlane_b32 s5, v255, 17
	v_readfirstlane_b32 s16, v4
	s_ashr_i32 s28, s16, 6
	s_lshl_b32 s26, s28, 5
	v_and_b32_e32 v102, 31, v4
	s_add_i32 s2, s26, s15
	v_or_b32_e32 v2, s2, v102
	v_ashrrev_i32_e32 v3, 31, v2
	v_lshl_add_u64 v[2:3], s[36:37], 0, v[2:3]
	v_lshlrev_b64 v[2:3], 11, v[2:3]
	s_mov_b32 s13, s1
	v_bfe_u32 v101, v4, 5, 1
	v_lshl_add_u64 v[2:3], s[4:5], 0, v[2:3]
	v_lshl_add_u64 v[2:3], v[2:3], 0, s[12:13]
	v_lshlrev_b32_e32 v0, 4, v101
	v_lshl_add_u64 v[2:3], v[2:3], 0, v[0:1]
	global_load_dwordx4 v[80:83], v[2:3], off
	global_load_dwordx4 v[84:87], v[2:3], off offset:32
	global_load_dwordx4 v[88:91], v[2:3], off offset:64
	global_load_dwordx4 v[92:95], v[2:3], off offset:96
	s_lshl_b32 s100, s3, 2
	v_mov_b32_e32 v245, s100
	global_load_dword v245, v245, s[10:11]
	v_cmp_gt_i32_e32 vcc, s27, v4
	s_and_saveexec_b64 s[4:5], vcc
	s_cbranch_execz .LBB0_548
	v_cmp_lt_i32_e32 vcc, 15, v4
	v_mov_b32_e32 v2, v4
	s_and_saveexec_b64 s[6:7], vcc
	s_cbranch_execz .LBB0_547
	v_cvt_f32_u32_e32 v2, v4
	v_mul_f32_e32 v2, 0x3d800000, v2
	v_cmp_gt_f32_e32 vcc, s97, v2
	s_nop 1
	v_cndmask_b32_e64 v3, 0, 32, vcc
	v_ldexp_f32 v2, v2, v3
	v_log_f32_e32 v2, v2
	v_mov_b32_e32 v3, 0x41b17218
	v_cndmask_b32_e32 v3, 0, v3, vcc
	v_mul_f32_e32 v5, 0x3f317217, v2
	v_fma_f32 v5, v2, s44, -v5
	v_fmac_f32_e32 v5, 0x3377d1cf, v2
	v_fmac_f32_e32 v5, 0x3f317217, v2
	v_cmp_lt_f32_e64 vcc, |v2|, s45
	s_nop 1
	v_cndmask_b32_e32 v2, v2, v5, vcc
	v_sub_f32_e32 v2, v2, v3
	v_div_scale_f32 v3, s[20:21], s46, s46, v2
	v_rcp_f32_e32 v5, v3
	v_div_scale_f32 v6, vcc, v2, s46, v2
	v_fma_f32 v7, -v3, v5, 1.0
	v_fmac_f32_e32 v5, v7, v5
	v_mul_f32_e32 v7, v6, v5
	v_fma_f32 v8, -v3, v7, v6
	v_fmac_f32_e32 v7, v8, v5
	v_fma_f32 v3, -v3, v7, v6
	v_div_fmas_f32 v3, v3, v5, v7
	v_div_fixup_f32 v2, v3, s46, v2
	v_mul_f32_e32 v2, 0x41800000, v2
	v_cvt_i32_f32_e32 v2, v2
	v_min_i32_e32 v2, 15, v2
	v_add_u32_e32 v2, 16, v2
.LBB0_547:
	s_or_b64 exec, exec, s[6:7]
	v_lshl_or_b32 v2, v2, 4, s3
	v_ashrrev_i32_e32 v3, 31, v2
	v_lshl_add_u64 v[2:3], v[2:3], 2, s[8:9]
	global_load_dword v243, v[2:3], off
	v_lshl_add_u32 v244, v4, 2, 0
	v_add_u32_e32 v244, 0x1ac40, v244
.LBB0_548:
	s_or_b64 exec, exec, s[4:5]
	v_ashrrev_i32_e32 v2, 3, v4
	v_ashrrev_i32_e32 v3, 31, v2
	v_lshl_add_u64 v[6:7], s[36:37], 0, v[2:3]
	v_readlane_b32 s4, v255, 20
	v_lshlrev_b64 v[6:7], 9, v[6:7]
	v_readlane_b32 s5, v255, 21
	s_lshl_b32 s0, s14, 1
	v_lshlrev_b32_e32 v3, 4, v4
	v_lshl_add_u64 v[8:9], s[4:5], 0, v[6:7]
	v_readlane_b32 s4, v255, 18
	v_readlane_b32 s5, v255, 19
	v_lshl_add_u64 v[8:9], v[8:9], 0, s[0:1]
	v_and_b32_e32 v38, 0x70, v3
	v_lshl_add_u64 v[6:7], s[4:5], 0, v[6:7]
	v_lshl_add_u64 v[6:7], v[6:7], 0, s[0:1]
	v_mov_b32_e32 v39, v1
	s_movk_i32 s0, 0xc0
	v_mad_u64_u32 v[40:41], s[4:5], v2, s0, v[38:39]
	s_and_b32 s6, s16, 0x3fffffc0
	v_add_u32_e32 v42, 0, v40
	s_movk_i32 s0, 0xffd0
	s_lshl_b32 s29, s24, 2
	v_mad_u64_u32 v[44:45], s[4:5], v2, s0, v[42:43]
	s_lshl_b32 s0, s6, 2
	s_or_b32 s7, s29, 3
	s_add_i32 s0, s0, 0
	v_lshl_add_u64 v[96:97], v[6:7], 0, v[38:39]
	v_lshl_add_u64 v[98:99], v[8:9], 0, v[38:39]
	s_add_i32 s21, s0, 0x1a440
	s_lshl_b32 s0, s7, 15
	s_or_b32 s4, s29, 2
	v_lshl_add_u64 v[6:7], v[96:97], 0, s[0:1]
	v_lshl_add_u64 v[10:11], v[98:99], 0, s[0:1]
	s_lshl_b32 s0, s4, 15
	s_or_b32 s5, s29, 1
	v_lshl_add_u64 v[14:15], v[96:97], 0, s[0:1]
	v_lshl_add_u64 v[18:19], v[98:99], 0, s[0:1]
	s_lshl_b32 s0, s5, 15
	v_lshl_add_u64 v[22:23], v[96:97], 0, s[0:1]
	v_lshl_add_u64 v[26:27], v[98:99], 0, s[0:1]
	s_lshl_b32 s0, s24, 17
	v_lshl_add_u64 v[30:31], v[96:97], 0, s[0:1]
	v_lshl_add_u64 v[34:35], v[98:99], 0, s[0:1]
	global_load_dwordx4 v[6:9], v[6:7], off
	s_ashr_i32 s13, s16, 7
	global_load_dwordx4 v[14:17], v[14:15], off
	v_and_b32_e32 v5, 63, v4
	global_load_dwordx4 v[18:21], v[18:19], off
	s_add_i32 s14, s13, s29
	global_load_dwordx4 v[22:25], v[22:23], off
	v_lshlrev_b32_e32 v3, 2, v101
	global_load_dwordx4 v[26:29], v[26:27], off
	s_nop 0
	global_load_dwordx4 v[30:33], v[30:31], off
	s_nop 0
	global_load_dwordx4 v[34:37], v[34:35], off
	s_nop 0
	global_load_dwordx4 v[10:13], v[10:11], off
	s_mul_i32 s0, s7, 52
	s_lshr_b32 s0, s0, 8
	s_mul_i32 s0, s0, 5
	s_sub_i32 s0, s7, s0
	s_and_b32 s0, s0, 0xff
	s_mul_i32 s6, s0, 0x2400
	v_add_u32_e32 v39, s6, v44
	s_mulk_i32 s0, 0x3000
	s_waitcnt vmcnt(7)
	v_cmp_gt_i32_e32 vcc, s27, v195
	s_and_saveexec_b64 s[100:101], vcc
	v_mul_f32_e32 v243, 0x3fb8aa3b, v243
	ds_write_b32 v244, v243
	s_or_b64 exec, exec, s[100:101]
	ds_write_b128 v39, v[6:9]
	v_add_u32_e32 v6, s0, v42
	s_mul_i32 s0, s4, 52
	s_lshr_b32 s0, s0, 8
	s_mul_i32 s0, s0, 5
	s_sub_i32 s0, s4, s0
	s_and_b32 s0, s0, 0xff
	s_mul_i32 s4, s0, 0x2400
	s_waitcnt vmcnt(0)
	ds_write_b128 v6, v[10:13] offset:46080
	v_add_u32_e32 v6, s4, v44
	s_mulk_i32 s0, 0x3000
	ds_write_b128 v6, v[14:17]
	v_add_u32_e32 v6, s0, v42
	s_mul_i32 s0, s5, 52
	s_lshr_b32 s0, s0, 8
	s_mul_i32 s0, s0, 5
	s_sub_i32 s0, s5, s0
	s_and_b32 s0, s0, 0xff
	s_mul_i32 s4, s0, 0x2400
	ds_write_b128 v6, v[18:21] offset:46080
	v_add_u32_e32 v6, s4, v44
	s_mulk_i32 s0, 0x3000
	ds_write_b128 v6, v[22:25]
	v_add_u32_e32 v6, s0, v42
	s_mul_i32 s0, s24, 0xd0
	s_lshr_b32 s0, s0, 8
	s_mul_i32 s0, s0, 5
	s_sub_i32 s0, s29, s0
	s_and_b32 s0, s0, 0xff
	s_mul_i32 s4, s0, 0x2400
	ds_write_b128 v6, v[26:29] offset:46080
	v_add_u32_e32 v6, s4, v44
	s_mulk_i32 s0, 0x3000
	v_lshrrev_b32_e32 v4, 2, v4
	ds_write_b128 v6, v[30:33]
	v_add_u32_e32 v6, s0, v42
	s_lshl_b32 s0, s28, 2
	v_lshlrev_b32_e32 v7, 2, v102
	v_and_or_b32 v4, v4, 3, v3
	s_add_i32 s20, s0, 0
	v_add_u32_e32 v104, s21, v7
	v_add_u32_e32 v103, s21, v0
	v_mul_u32_u24_e32 v4, 0xc0, v4
	s_mul_i32 s0, s24, 0xc000
	s_mul_i32 s21, s13, 0x3000
	v_or_b32_e32 v4, s21, v4
	s_add_i32 s21, s0, 0
	s_mul_i32 s0, s24, 0x9000
	s_movk_i32 s25, 0x90
	s_mul_i32 s30, s13, 0x2400
	s_add_i32 s24, s0, 0xffffdc00
	v_mul_lo_u32 v2, v2, s25
	s_add_i32 s30, s30, s0
	s_sub_i32 s0, s26, 59
	v_add3_u32 v121, s24, v2, v38
	v_add_u32_e32 v2, s0, v102
	v_cmp_eq_u32_e64 s[4:5], 0, v5
	v_cmp_gt_u32_e64 s[6:7], 32, v5
	v_lshlrev_b32_e32 v8, 1, v5
	v_lshlrev_b32_e32 v5, 3, v5
	s_lshl_b32 s25, s13, 6
	v_sub_u32_e32 v2, v2, v3
	v_and_b32_e32 v8, 32, v8
	v_and_b32_e32 v5, 24, v5
	v_subrev_u32_e32 v124, s25, v2
	v_add_u32_e32 v2, s26, v102
	v_or3_b32 v4, v4, v8, v5
	v_sub_u32_e32 v2, v2, v3
	v_add_u32_e32 v105, 0xde40, v4
	v_add_u32_e32 v106, 0xd840, v4
	v_add_u32_e32 v107, 0xde00, v4
	v_add_u32_e32 v108, 0xd800, v4
	v_add_u32_e32 v109, 0xd240, v4
	v_add_u32_e32 v110, 0xcc40, v4
	v_add_u32_e32 v111, 0xd200, v4
	v_add_u32_e32 v112, 0xcc00, v4
	v_add_u32_e32 v113, 0xc640, v4
	v_add_u32_e32 v114, 0xc040, v4
	v_add_u32_e32 v115, 0xc600, v4
	v_add_u32_e32 v116, 0xc000, v4
	v_add_u32_e32 v117, 0xba40, v4
	v_add_u32_e32 v118, 0xb440, v4
	v_add_u32_e32 v119, 0xba00, v4
	v_add_u32_e32 v120, 0xb400, v4
	v_subrev_u32_e32 v2, s25, v2
	v_mov_b32_e32 v4, 0x1ac40
	ds_write_b128 v6, v[34:37] offset:46080
	v_mul_u32_u24_e32 v6, 0x90, v102
	v_lshl_add_u32 v125, v2, 2, v4
	v_lshl_or_b32 v2, s28, 7, v7
	v_add3_u32 v123, s30, v6, v0
	v_sub_u32_e32 v0, v2, v0
	s_lshl_b32 s0, s13, 8
	v_subrev_u32_e32 v126, s0, v0
	v_sub_u32_e32 v0, v3, v102
	v_mov_b32_e32 v14, v1
	v_mov_b32_e32 v15, v1
	v_add_u32_e32 v122, 0x8400, v40
	v_subrev_u32_e32 v127, s26, v0
	v_mov_b32_e32 v0, v1
	v_mov_b32_e32 v2, v1
	v_mov_b32_e32 v3, v1
	v_mov_b32_e32 v4, v1
	v_mov_b32_e32 v5, v1
	v_mov_b32_e32 v6, v1
	v_mov_b32_e32 v7, v1
	v_mov_b32_e32 v8, v1
	v_mov_b32_e32 v9, v1
	v_mov_b32_e32 v10, v1
	v_mov_b32_e32 v11, v1
	v_mov_b32_e32 v12, v1
	v_mov_b32_e32 v13, v1
	v_mov_b64_e32 v[30:31], v[14:15]
	v_mov_b64_e32 v[46:47], v[14:15]
	s_add_i32 s16, s2, 0xffffff81
	s_mov_b32 s17, 0
	s_add_i32 s20, s20, 0x1a400
	s_add_i32 s24, s29, -1
	v_mov_b32_e32 v129, 0xff800000
	v_mov_b32_e32 v128, 0
	s_mov_b32 s26, 0
	v_mov_b64_e32 v[28:29], v[12:13]
	v_mov_b64_e32 v[26:27], v[10:11]
	v_mov_b64_e32 v[24:25], v[8:9]
	v_mov_b64_e32 v[22:23], v[6:7]
	v_mov_b64_e32 v[20:21], v[4:5]
	v_mov_b64_e32 v[18:19], v[2:3]
	v_mov_b64_e32 v[16:17], v[0:1]
	v_mov_b64_e32 v[44:45], v[12:13]
	v_mov_b64_e32 v[42:43], v[10:11]
	v_mov_b64_e32 v[40:41], v[8:9]
	v_mov_b64_e32 v[38:39], v[6:7]
	v_mov_b64_e32 v[36:37], v[4:5]
	v_mov_b64_e32 v[34:35], v[2:3]
	v_mov_b64_e32 v[32:33], v[0:1]
	s_waitcnt lgkmcnt(0)
	s_barrier

.LBB0_628:
	ds_bpermute_b32 v0, v100, v128
	s_and_saveexec_b64 s[4:5], s[6:7]
	s_cbranch_execz .LBB0_457
	s_lshl_b32 s0, s3, 2
	s_waitcnt vmcnt(0)
	s_nop 0
	s_nop 0
	s_waitcnt lgkmcnt(0)
	v_add_f32_e32 v0, v128, v0
	s_waitcnt vmcnt(0)
	v_fma_f32 v2, v245, s68, -v51
	v_exp_f32_e32 v2, v2
	s_nop 0
	v_add_f32_e32 v0, v0, v2
	v_div_scale_f32 v2, s[6:7], v0, v0, 1.0
	v_rcp_f32_e32 v3, v2
	v_div_scale_f32 v4, vcc, 1.0, v0, 1.0
	v_fma_f32 v5, -v2, v3, 1.0
	v_fmac_f32_e32 v3, v5, v3
	v_mul_f32_e32 v5, v4, v3
	v_fma_f32 v6, -v2, v5, v4
	v_fmac_f32_e32 v5, v6, v3
	v_fma_f32 v2, -v2, v5, v4
	v_div_fmas_f32 v2, v2, v3, v5
	v_div_fixup_f32 v0, v2, v0, 1.0
	ds_write_b32 v104, v0
	s_branch .LBB0_457

.LBB0_770:
	s_or_b64 exec, exec, s[6:7]
	s_mov_b32 s2, 0
	s_mov_b32 s0, 0
	s_mov_b32 s12, s1
	v_and_b32_e32 v0, 0xff, v195
	v_lshrrev_b32_e32 v251, 8, v195
	s_movk_i32 s3, 0x100
	s_waitcnt lgkmcnt(0)
	s_barrier
	s_nop 0
	v_cmp_gt_i32_e32 vcc, s3, v0
	s_and_saveexec_b64 s[6:7], vcc
	s_cbranch_execz .LBB0_779
	s_ashr_i32 s3, s0, 31
	s_add_u32 s0, s62, s0
	s_addc_u32 s3, s63, s3
	s_lshl_b64 s[4:5], s[4:5], 2
	s_add_u32 s4, s0, s4
	v_mov_b32_e32 v2, 0x20400
	s_addc_u32 s5, s3, s5
	v_lshl_add_u32 v2, v0, 2, v2
	v_lshl_add_u32 v2, v251, 10, v2
	s_mov_b64 s[8:9], s[88:89]
	v_readfirstlane_b32 s100, v251
	s_mul_i32 s100, s100, s94
	s_add_u32 s8, s8, s100
	s_addc_u32 s9, s9, 0
	s_branch .LBB0_774
.LBB0_772:
	s_ashr_i32 s0, s0, 3
	s_add_i32 s0, s13, s0
	s_ashr_i32 s3, s0, 31
	s_lshr_b32 s3, s3, 25
	s_add_i32 s3, s0, s3
	s_ashr_i32 s10, s3, 7
	s_lshl_b32 s10, s10, 3
	s_sub_i32 s11, 0x80, s10
	s_min_i32 s11, s11, 8
	s_abs_i32 s11, s11
	v_cvt_f32_u32_e32 v3, s11
	s_sub_i32 s13, 0, s11
	s_and_b32 s3, s3, 0xffffff80
	s_sub_i32 s0, s0, s3
	v_rcp_iflag_f32_e32 v3, v3
	s_ashr_i32 s3, s0, 31
	s_abs_i32 s0, s0
	v_mul_f32_e32 v3, 0x4f7ffffe, v3
	v_cvt_u32_f32_e32 v3, v3
	s_nop 0
	v_readfirstlane_b32 s14, v3
	s_mul_i32 s13, s13, s14
	s_mul_hi_u32 s13, s14, s13
	s_add_i32 s14, s14, s13
	s_mul_hi_u32 s13, s0, s14
	s_mul_i32 s13, s13, s11
	s_sub_i32 s0, s0, s13
	s_sub_i32 s13, s0, s11
	s_cmp_ge_u32 s0, s11
	s_cselect_b32 s0, s13, s0
	s_sub_i32 s13, s0, s11
	s_cmp_ge_u32 s0, s11
	s_cselect_b32 s0, s13, s0
	s_xor_b32 s0, s0, s3
	s_sub_i32 s0, s0, s3
	s_add_i32 s10, s10, s0
	v_lshl_add_u32 v4, s10, 8, v0
	v_ashrrev_i32_e32 v5, 31, v4
	v_lshlrev_b64 v[4:5], 6, v[4:5]
	v_lshl_add_u64 v[16:17], s[4:5], 0, v[4:5]
	global_load_dwordx4 v[4:7], v[16:17], off
	global_load_dwordx4 v[8:11], v[16:17], off offset:32
	global_load_dwordx4 v[12:15], v[16:17], off offset:16
	s_nop 0
	global_load_dwordx4 v[16:19], v[16:17], off offset:48
	s_add_u32 s8, s8, s94
	s_addc_u32 s9, s9, s77
	s_add_u32 s8, s8, s94
	s_addc_u32 s9, s9, s77
	s_mov_b64 s[10:11], 0
	s_waitcnt vmcnt(3)
	v_mov_b32_e32 v20, v4
	s_waitcnt vmcnt(2)
	v_mov_b32_e32 v21, v8
	v_mov_b32_e32 v8, v5
	v_mov_b32_e32 v4, v6
	v_mov_b32_e32 v5, v10
	v_mov_b32_e32 v10, v7
	s_waitcnt vmcnt(1)
	v_mov_b32_e32 v6, v12
	s_waitcnt vmcnt(0)
	v_mov_b32_e32 v7, v16
	v_mov_b32_e32 v16, v13
	v_mov_b32_e32 v12, v14
	v_mov_b32_e32 v13, v18
	v_mov_b32_e32 v18, v15
	v_pk_add_f32 v[8:9], v[20:21], v[8:9]
	v_pk_add_f32 v[4:5], v[4:5], v[10:11]
	v_pk_add_f32 v[6:7], v[6:7], v[16:17]
	v_pk_add_f32 v[10:11], v[12:13], v[18:19]
	v_pk_add_f32 v[4:5], v[8:9], v[4:5]
	v_pk_add_f32 v[6:7], v[6:7], v[10:11]
	s_nop 0
	v_pk_add_f32 v[4:5], v[4:5], v[6:7]
	s_nop 0
	v_add_f32_e32 v3, v4, v5
	v_mov_b32_e32 v4, 0x358637bd
	v_fmamk_f32 v3, v3, 0x3a800000, v4
	v_mul_f32_e32 v4, 0x4b800000, v3
	v_cmp_gt_f32_e32 vcc, s97, v3
	s_nop 1
	v_cndmask_b32_e32 v3, v3, v4, vcc
	v_rsq_f32_e32 v3, v3
	s_nop 0
	v_mul_f32_e32 v4, 0x45800000, v3
	v_cndmask_b32_e32 v3, v3, v4, vcc
	ds_write_b32 v2, v3
	v_add_u32_e32 v2, 0x800, v2

.LBB0_964:
	s_mov_b32 s12, 0
	s_mov_b32 s3, 0
	s_mov_b32 s2, 0
	s_mov_b32 s6, 0
	s_mov_b32 s0, s1
	v_and_b32_e32 v0, 0xff, v195
	v_lshrrev_b32_e32 v251, 8, v195
	s_movk_i32 s4, 0x100
	s_nop 0
	v_cmp_gt_i32_e32 vcc, s4, v0
	s_and_saveexec_b64 s[4:5], vcc
	s_cbranch_execz .LBB0_973
	s_ashr_i32 s7, s6, 31
	s_add_u32 s10, s62, s6
	s_addc_u32 s11, s63, s7
	s_lshl_b64 s[6:7], s[8:9], 2
	s_add_u32 s6, s10, s6
	v_mov_b32_e32 v2, 0x20400
	s_addc_u32 s7, s11, s7
	v_lshl_add_u32 v2, v0, 2, v2
	v_lshl_add_u32 v2, v251, 10, v2
	s_mov_b64 s[8:9], s[88:89]
	v_readfirstlane_b32 s100, v251
	s_mul_i32 s100, s100, s94
	s_add_u32 s8, s8, s100
	s_addc_u32 s9, s9, 0
	s_branch .LBB0_968
.LBB0_966:
	s_ashr_i32 s10, s13, 3
	s_add_i32 s10, s15, s10
	s_ashr_i32 s11, s10, 31
	s_lshr_b32 s11, s11, 27
	s_add_i32 s11, s10, s11
	s_ashr_i32 s13, s11, 5
	s_lshl_b32 s13, s13, 3
	s_sub_i32 s14, 0x80, s13
	s_min_i32 s14, s14, 8
	s_abs_i32 s14, s14
	v_cvt_f32_u32_e32 v3, s14
	s_sub_i32 s15, 0, s14
	s_andn2_b32 s11, s11, 31
	s_sub_i32 s10, s10, s11
	v_rcp_iflag_f32_e32 v3, v3
	s_ashr_i32 s11, s10, 31
	s_abs_i32 s10, s10
	v_mul_f32_e32 v3, 0x4f7ffffe, v3
	v_cvt_u32_f32_e32 v3, v3
	s_nop 0
	v_readfirstlane_b32 s16, v3
	s_mul_i32 s15, s15, s16
	s_mul_hi_u32 s15, s16, s15
	s_add_i32 s16, s16, s15
	s_mul_hi_u32 s15, s10, s16
	s_mul_i32 s15, s15, s14
	s_sub_i32 s10, s10, s15
	s_sub_i32 s15, s10, s14
	s_cmp_ge_u32 s10, s14
	s_cselect_b32 s10, s15, s10
	s_sub_i32 s15, s10, s14
	s_cmp_ge_u32 s10, s14
	s_cselect_b32 s10, s15, s10
	s_xor_b32 s10, s10, s11
	s_sub_i32 s10, s10, s11
	s_add_i32 s13, s13, s10
	v_lshl_add_u32 v4, s13, 8, v0
	v_ashrrev_i32_e32 v5, 31, v4
	v_lshlrev_b64 v[4:5], 6, v[4:5]
	v_lshl_add_u64 v[16:17], s[6:7], 0, v[4:5]
	global_load_dwordx4 v[4:7], v[16:17], off
	global_load_dwordx4 v[8:11], v[16:17], off offset:32
	global_load_dwordx4 v[12:15], v[16:17], off offset:16
	s_nop 0
	global_load_dwordx4 v[16:19], v[16:17], off offset:48
	s_add_u32 s8, s8, s94
	s_addc_u32 s9, s9, s77
	s_add_u32 s8, s8, s94
	s_addc_u32 s9, s9, s77
	s_mov_b64 s[10:11], 0
	s_waitcnt vmcnt(0)
	v_mov_b32_e32 v20, v4
	v_mov_b32_e32 v21, v8
	v_mov_b32_e32 v8, v5
	v_mov_b32_e32 v4, v6
	v_mov_b32_e32 v5, v10
	v_mov_b32_e32 v10, v7
	v_mov_b32_e32 v6, v12
	v_mov_b32_e32 v7, v16
	v_mov_b32_e32 v16, v13
	v_mov_b32_e32 v12, v14
	v_mov_b32_e32 v13, v18
	v_mov_b32_e32 v18, v15
	v_pk_add_f32 v[8:9], v[20:21], v[8:9]
	v_pk_add_f32 v[4:5], v[4:5], v[10:11]
	v_pk_add_f32 v[6:7], v[6:7], v[16:17]
	v_pk_add_f32 v[10:11], v[12:13], v[18:19]
	v_pk_add_f32 v[4:5], v[8:9], v[4:5]
	v_pk_add_f32 v[6:7], v[6:7], v[10:11]
	s_nop 0
	v_pk_add_f32 v[4:5], v[4:5], v[6:7]
	s_nop 0
	v_add_f32_e32 v3, v4, v5
	v_mov_b32_e32 v4, 0x358637bd
	v_fmamk_f32 v3, v3, 0x3a800000, v4
	v_mul_f32_e32 v4, 0x4b800000, v3
	v_cmp_gt_f32_e32 vcc, s97, v3
	s_nop 1
	v_cndmask_b32_e32 v3, v3, v4, vcc
	v_rsq_f32_e32 v3, v3
	s_nop 0
	v_mul_f32_e32 v4, 0x45800000, v3
	v_cndmask_b32_e32 v3, v3, v4, vcc
	ds_write_b32 v2, v3
	v_add_u32_e32 v2, 0x800, v2
